# v28 + diff attention loop: QK MFMAs reordered (s0 accumulation chain first) so the first 16 exps and the V^T fragment reads issue between the s1 chain MFMAs on far tiles
# baseline (speedup 1.0000x reference)
; #define ALAS __attribute__((address_space(3)))
; __device__ __forceinline__ void qk_tile(f32x16& s0, f32x16& s1, float ci, const ALAS unsigned char* Kb, const bf16x8 (&qf)[4], int r32, int hi) {
;     const unsigned p0 = (unsigned)(uintptr_t)(Kb + kperm(r32) * ROWB + hi * 16);
;     bf16x8 a[8];
;     ldsr<0>(a[0], p0); ldsr<32 * ROWB>(a[1], p0); ldsr<32>(a[2], p0); ldsr<32 * ROWB + 32>(a[3], p0);
;     ldsr<64>(a[4], p0); ldsr<32 * ROWB + 64>(a[5], p0); ldsr<96>(a[6], p0); ldsr<32 * ROWB + 96>(a[7], p0);
; #pragma unroll
;     for (int r = 0; r < 16; ++r) { s0[r] = ci; s1[r] = ci; }
;     lds_wait8(a); __builtin_amdgcn_sched_barrier(0);
; #pragma unroll
;     for (int d0 = 0; d0 < 4; ++d0) {
;         s0 = __builtin_amdgcn_mfma_f32_32x32x16_bf16(a[2 * d0], qf[d0], s0, 0, 0, 0);
;         s1 = __builtin_amdgcn_mfma_f32_32x32x16_bf16(a[2 * d0 + 1], qf[d0], s1, 0, 0, 0);
;     }
; }
; template <int NDB, int KB>
; __device__ __forceinline__ void issue_v(bf16x8 (&v)[2 * NDB], unsigned vp) {
;     ldsr<0 * 32 * ROWB + 64 * KB>(v[0], vp); ldsr<1 * 32 * ROWB + 64 * KB>(v[1], vp);
;     if constexpr (NDB == 4) { ldsr<2 * 32 * ROWB + 64 * KB>(v[2], vp); ldsr<3 * 32 * ROWB + 64 * KB>(v[3], vp); }
;     ldsr<0 * 32 * ROWB + 64 * KB + 32>(v[NDB + 0], vp); ldsr<1 * 32 * ROWB + 64 * KB + 32>(v[NDB + 1], vp);
;     if constexpr (NDB == 4) { ldsr<2 * 32 * ROWB + 64 * KB + 32>(v[NDB + 2], vp); ldsr<3 * 32 * ROWB + 64 * KB + 32>(v[NDB + 3], vp); }
; }
; __device__ __forceinline__ void pack16(const f32x16& s, bf16x8& pf0, bf16x8& pf1) {
;     u32x4 w0, w1;
;     w0.x = cvtpk(s[0], s[1]); w0.y = cvtpk(s[2], s[3]); w0.z = cvtpk(s[4], s[5]); w0.w = cvtpk(s[6], s[7]);
;     w1.x = cvtpk(s[8], s[9]); w1.y = cvtpk(s[10], s[11]); w1.z = cvtpk(s[12], s[13]); w1.w = cvtpk(s[14], s[15]);
;     pf0 = __builtin_bit_cast(bf16x8, w0); pf1 = __builtin_bit_cast(bf16x8, w1);
; }
; __device__ __forceinline__ void near_bias(f32x16& s0, f32x16& s1, const ALAS float* bt, int qpos, int kbase, int hi) {
; #pragma unroll
;     for (int r = 0; r < 16; ++r) {
;         const int d0 = qpos - (kbase + (r & 7) + 8 * hi + 16 * (r >> 3)), d1 = d0 - 32;
;         const float b0 = bt[min(max(d0, 0), 255)], b1 = bt[min(max(d1, 0), 255)];
;         s0[r] = d0 < 0 ? NEG : s0[r] + b0; s1[r] = d1 < 0 ? NEG : s1[r] + b1;
;     }
; }
; __device__ __forceinline__ void anchor(f32x16& s0, f32x16& s1, float& mref) {
.LBB0_504:
	s_bitcmp1_b32 s14, 0
	s_cselect_b32 s4, 0, 0x9000
	s_add_i32 s18, s4, 0
	v_add_u32_e32 v64, s18, v138
	s_waitcnt vmcnt(3)
	ds_write_b128 v64, v[112:115]
	v_add_u32_e32 v64, s18, v158
	s_waitcnt vmcnt(1)
	ds_write_b128 v64, v[116:119] offset:18432
	v_add_u32_e32 v64, s18, v142
	s_waitcnt vmcnt(1)
	ds_write_b128 v64, v[120:123]
	v_add_u32_e32 v64, s18, v160
	s_cmp_ge_i32 s14, s16
	s_waitcnt vmcnt(0)
	ds_write_b128 v64, v[124:127] offset:18432
	s_waitcnt lgkmcnt(0)
	s_barrier
	v_add_u32_e32 v144, s18, v139
	v_add3_u32 v144, s11, v144, v130
	ds_read_b128 v[172:175], v144 offset:0
	ds_read_b128 v[180:183], v144 offset:32
	ds_read_b128 v[188:191], v144 offset:64
	ds_read_b128 v[196:199], v144 offset:96
	ds_read_b128 v[176:179], v144 offset:4608
	ds_read_b128 v[184:187], v144 offset:4640
	ds_read_b128 v[192:195], v144 offset:4672
	ds_read_b128 v[216:219], v144 offset:4704
	s_cbranch_scc1 .LBB0_506
	s_add_i32 s4, s17, 64
	s_lshl_b64 s[36:37], s[4:5], 1
	v_lshl_add_u64 v[64:65], v[156:157], 0, s[36:37]
	v_lshl_add_u64 v[66:67], v[140:141], 0, s[36:37]
	global_load_dwordx4 v[112:115], v[164:165], off
	global_load_dwordx4 v[120:123], v[166:167], off
	global_load_dwordx4 v[116:119], v[66:67], off
	global_load_dwordx4 v[124:127], v[64:65], off
.LBB0_506:
	s_cmp_gt_i32 s17, s15
	s_cbranch_scc1 .LBB0_503
	s_cmpk_gt_i32 s12, 0x7f
	s_cselect_b64 vcc, -1, 0
	s_nop 1
	v_cndmask_b32_e32 v64, 0, v137, vcc
	v_sub_f32_e32 v64, v64, v163
	v_mov_b32_e32 v65, v64
	v_mov_b32_e32 v66, v64
	v_mov_b32_e32 v67, v64
	v_mov_b32_e32 v68, v64
	v_mov_b32_e32 v69, v64
	v_mov_b32_e32 v70, v64
	v_mov_b32_e32 v71, v64
	v_mov_b32_e32 v72, v64
	v_mov_b32_e32 v73, v64
	v_mov_b32_e32 v74, v64
	v_mov_b32_e32 v75, v64
	v_mov_b32_e32 v76, v64
	v_mov_b32_e32 v77, v64
	v_mov_b32_e32 v78, v64
	v_mov_b32_e32 v79, v64
	s_waitcnt lgkmcnt(6)
	s_nop 1
	v_mfma_f32_32x32x16_bf16 v[80:95], v[172:175], v[108:111], v[64:79]
	s_and_b64 vcc, exec, vcc
	v_mfma_f32_32x32x16_bf16 v[80:95], v[180:183], v[104:107], v[80:95]
	s_waitcnt lgkmcnt(4)
	v_mfma_f32_32x32x16_bf16 v[80:95], v[188:191], v[100:103], v[80:95]
	v_mfma_f32_32x32x16_bf16 v[80:95], v[196:199], v[96:99], v[80:95]
	s_waitcnt lgkmcnt(0)
	v_mfma_f32_32x32x16_bf16 v[64:79], v[176:179], v[108:111], v[64:79]
	s_cbranch_vccz .Lnear_d
	v_add_u32_e32 v144, s18, v143
	v_add3_u32 v144, v144, v130, s35
	ds_read_b128 v[172:175], v144 offset:0
	ds_read_b128 v[180:183], v144 offset:9216
	ds_read_b128 v[188:191], v144 offset:32
	ds_read_b128 v[196:199], v144 offset:9248
	ds_read_b128 v[176:179], v144 offset:4608
	v_mfma_f32_32x32x16_bf16 v[64:79], v[184:187], v[104:107], v[64:79]
	ds_read_b128 v[184:187], v144 offset:13824
	s_nop 1
	v_exp_f32_e32 v248, v88
	v_exp_f32_e32 v249, v89
	v_exp_f32_e32 v250, v90
	v_exp_f32_e32 v251, v91
	v_mfma_f32_32x32x16_bf16 v[64:79], v[192:195], v[100:103], v[64:79]
	ds_read_b128 v[192:195], v144 offset:4640
	v_exp_f32_e32 v252, v92
	v_exp_f32_e32 v253, v93
	v_exp_f32_e32 v215, v94
	v_exp_f32_e32 v207, v95
	v_mfma_f32_32x32x16_bf16 v[64:79], v[216:219], v[96:99], v[64:79]
	ds_read_b128 v[216:219], v144 offset:13856
	v_exp_f32_e32 v161, v80
	v_exp_f32_e32 v168, v81
	v_exp_f32_e32 v169, v82
	v_exp_f32_e32 v171, v83
	v_exp_f32_e32 v244, v84
	v_exp_f32_e32 v245, v85
	v_exp_f32_e32 v246, v86
	v_exp_f32_e32 v247, v87
	ds_read_b128 v[88:91], v144 offset:64
	ds_read_b128 v[92:95], v144 offset:4672
	ds_read_b128 v[220:223], v144 offset:9280
	ds_read_b128 v[224:227], v144 offset:13888
	ds_read_b128 v[228:231], v144 offset:96
	ds_read_b128 v[232:235], v144 offset:4704
	ds_read_b128 v[236:239], v144 offset:9312
	ds_read_b128 v[240:243], v144 offset:13920
	v_cvt_pk_bf16_f32 v80, v161, v168
	v_cvt_pk_bf16_f32 v81, v169, v171
	v_cvt_pk_bf16_f32 v82, v244, v245
	v_cvt_pk_bf16_f32 v83, v246, v247
	v_cvt_pk_bf16_f32 v84, v248, v249
	v_cvt_pk_bf16_f32 v85, v250, v251
	v_cvt_pk_bf16_f32 v86, v252, v253
	v_cvt_pk_bf16_f32 v87, v215, v207
	s_branch .Lpv_d
.Lnear_d:
	v_mfma_f32_32x32x16_bf16 v[64:79], v[184:187], v[104:107], v[64:79]
	v_mfma_f32_32x32x16_bf16 v[64:79], v[192:195], v[100:103], v[64:79]
	v_mfma_f32_32x32x16_bf16 v[64:79], v[216:219], v[96:99], v[64:79]
	v_add_u32_e32 v161, s12, v159
	v_add_u32_e32 v171, 63, v161
	v_add_u32_e32 v161, 62, v161
	v_med3_i32 v172, v161, 0, v204
	v_lshl_add_u32 v173, v172, 2, s10
	v_max_i32_e32 v172, 32, v161
	v_add_u32_e32 v144, s17, v134
	v_subrev_u32_e32 v172, 32, v172
	v_min_u32_e32 v172, 0xff, v172
	v_or_b32_e32 v175, 2, v144
	v_lshl_add_u32 v174, v172, 2, s10
	v_or_b32_e32 v172, 3, v144
	v_sub_u32_e32 v219, v136, v175
	v_sub_u32_e32 v218, v131, v172
	v_med3_i32 v172, v219, 0, v204
	v_lshl_add_u32 v175, v172, 2, s10
	v_max_i32_e32 v172, 32, v219
	v_subrev_u32_e32 v172, 32, v172
	v_min_u32_e32 v172, 0xff, v172
	v_lshl_add_u32 v176, v172, 2, s10
	v_max_i32_e32 v172, 32, v218
	v_max_i32_e32 v169, 32, v171
	v_subrev_u32_e32 v172, 32, v172
	v_subrev_u32_e32 v169, 32, v169
	v_min_u32_e32 v172, 0xff, v172
	v_med3_i32 v168, v171, 0, v204
	v_min_u32_e32 v169, 0xff, v169
	v_lshl_add_u32 v177, v172, 2, s10
	v_med3_i32 v172, v218, 0, v204
	v_lshl_add_u32 v168, v168, 2, s10
	v_lshl_add_u32 v169, v169, 2, s10
	v_lshl_add_u32 v178, v172, 2, s10
	ds_read_b32 v172, v168
	ds_read_b32 v168, v169
	ds_read_b32 v173, v173
	ds_read_b32 v169, v174
	ds_read_b32 v174, v175
	ds_read_b32 v176, v176
	ds_read_b32 v177, v177
	ds_read_b32 v175, v178
	v_or_b32_e32 v178, 5, v144
	v_sub_u32_e32 v220, v131, v178
	v_max_i32_e32 v180, 32, v220
	v_subrev_u32_e32 v180, 32, v180
	v_min_u32_e32 v180, 0xff, v180
	v_lshl_add_u32 v181, v180, 2, s10
	v_med3_i32 v180, v220, 0, v204
	v_or_b32_e32 v183, 6, v144
	v_lshl_add_u32 v182, v180, 2, s10
; #define ALAS __attribute__((address_space(3)))
; __device__ __forceinline__ void near_bias(f32x16& s0, f32x16& s1, const ALAS float* bt, int qpos, int kbase, int hi) {
; #pragma unroll
;     for (int r = 0; r < 16; ++r) {
;         const int d0 = qpos - (kbase + (r & 7) + 8 * hi + 16 * (r >> 3)), d1 = d0 - 32;
;         const float b0 = bt[min(max(d0, 0), 255)], b1 = bt[min(max(d1, 0), 255)];
;         s0[r] = d0 < 0 ? NEG : s0[r] + b0; s1[r] = d1 < 0 ? NEG : s1[r] + b1;
;     }
; }
	v_or_b32_e32 v180, 7, v144
	v_sub_u32_e32 v223, v136, v183
	v_sub_u32_e32 v222, v131, v180
	v_med3_i32 v180, v223, 0, v204
	v_lshl_add_u32 v183, v180, 2, s10
	v_max_i32_e32 v180, 32, v223
	v_subrev_u32_e32 v180, 32, v180
	v_or_b32_e32 v179, 4, v144
	v_min_u32_e32 v180, 0xff, v180
	v_sub_u32_e32 v221, v136, v179
	v_lshl_add_u32 v184, v180, 2, s10
	v_max_i32_e32 v180, 32, v222
	v_max_i32_e32 v179, 32, v221
	v_subrev_u32_e32 v180, 32, v180
	v_subrev_u32_e32 v179, 32, v179
	v_min_u32_e32 v180, 0xff, v180
	v_med3_i32 v178, v221, 0, v204
	v_min_u32_e32 v179, 0xff, v179
	v_lshl_add_u32 v185, v180, 2, s10
	v_med3_i32 v180, v222, 0, v204
	v_lshl_add_u32 v178, v178, 2, s10
	v_lshl_add_u32 v179, v179, 2, s10
	v_lshl_add_u32 v186, v180, 2, s10
	ds_read_b32 v178, v178
	ds_read_b32 v180, v179
	ds_read_b32 v181, v181
	ds_read_b32 v179, v182
	ds_read_b32 v182, v183
	ds_read_b32 v184, v184
	ds_read_b32 v185, v185
	ds_read_b32 v183, v186
	v_or_b32_e32 v186, 17, v144
	v_sub_u32_e32 v224, v131, v186
	v_max_i32_e32 v188, 32, v224
	v_subrev_u32_e32 v188, 32, v188
	v_min_u32_e32 v188, 0xff, v188
	v_lshl_add_u32 v189, v188, 2, s10
	v_med3_i32 v188, v224, 0, v204
	v_or_b32_e32 v191, 18, v144
	v_lshl_add_u32 v190, v188, 2, s10
	v_or_b32_e32 v188, 19, v144
	v_sub_u32_e32 v227, v136, v191
	v_sub_u32_e32 v226, v131, v188
	v_med3_i32 v188, v227, 0, v204
	v_lshl_add_u32 v191, v188, 2, s10
	v_max_i32_e32 v188, 32, v227
	v_subrev_u32_e32 v188, 32, v188
	v_or_b32_e32 v187, 16, v144
	v_min_u32_e32 v188, 0xff, v188
	v_sub_u32_e32 v225, v136, v187
	v_lshl_add_u32 v192, v188, 2, s10
	v_max_i32_e32 v188, 32, v226
	v_max_i32_e32 v187, 32, v225
	v_subrev_u32_e32 v188, 32, v188
	v_subrev_u32_e32 v187, 32, v187
	v_min_u32_e32 v188, 0xff, v188
	v_med3_i32 v186, v225, 0, v204
	v_min_u32_e32 v187, 0xff, v187
	v_lshl_add_u32 v193, v188, 2, s10
	v_med3_i32 v188, v226, 0, v204
	v_lshl_add_u32 v186, v186, 2, s10
	v_lshl_add_u32 v187, v187, 2, s10
	v_lshl_add_u32 v194, v188, 2, s10
	ds_read_b32 v186, v186
	ds_read_b32 v188, v187
	ds_read_b32 v189, v189
	ds_read_b32 v187, v190
	ds_read_b32 v190, v191
	ds_read_b32 v192, v192
	ds_read_b32 v193, v193
	ds_read_b32 v191, v194
	v_or_b32_e32 v194, 21, v144
	v_sub_u32_e32 v228, v131, v194
	v_max_i32_e32 v196, 32, v228
	v_subrev_u32_e32 v196, 32, v196
	v_min_u32_e32 v196, 0xff, v196
	v_lshl_add_u32 v197, v196, 2, s10
	v_med3_i32 v196, v228, 0, v204
	v_or_b32_e32 v195, 20, v144
	v_lshl_add_u32 v198, v196, 2, s10
	v_or_b32_e32 v196, 23, v144
	v_or_b32_e32 v144, 22, v144
	v_sub_u32_e32 v144, v136, v144
	v_sub_u32_e32 v230, v131, v196
	v_med3_i32 v196, v144, 0, v204
	v_lshl_add_u32 v199, v196, 2, s10
	v_max_i32_e32 v196, 32, v144
	v_subrev_u32_e32 v196, 32, v196
	v_sub_u32_e32 v229, v136, v195
	v_min_u32_e32 v196, 0xff, v196
	v_max_i32_e32 v195, 32, v229
	v_lshl_add_u32 v216, v196, 2, s10
	v_max_i32_e32 v196, 32, v230
	v_subrev_u32_e32 v195, 32, v195
	v_subrev_u32_e32 v196, 32, v196
	v_med3_i32 v194, v229, 0, v204
	v_min_u32_e32 v195, 0xff, v195
	v_min_u32_e32 v196, 0xff, v196
	v_lshl_add_u32 v194, v194, 2, s10
	v_lshl_add_u32 v195, v195, 2, s10
	v_lshl_add_u32 v217, v196, 2, s10
	v_med3_i32 v196, v230, 0, v204
	v_lshl_add_u32 v231, v196, 2, s10
	ds_read_b32 v194, v194
	ds_read_b32 v196, v195
	ds_read_b32 v197, v197
	ds_read_b32 v195, v198
	ds_read_b32 v198, v199
	ds_read_b32 v216, v216
	ds_read_b32 v217, v217
	ds_read_b32 v199, v231
	v_cmp_lt_i32_e32 vcc, -1, v230
	s_waitcnt lgkmcnt(4)
	v_pk_add_f32 v[92:93], v[92:93], v[194:195]
	v_pk_add_f32 v[90:91], v[90:91], v[190:191]
	v_pk_add_f32 v[88:89], v[88:89], v[186:187]
	s_waitcnt lgkmcnt(0)
	v_pk_add_f32 v[94:95], v[94:95], v[198:199]
	v_pk_add_f32 v[86:87], v[86:87], v[182:183]
	v_cndmask_b32_e32 v95, v205, v95, vcc
	v_cmp_lt_i32_e32 vcc, -1, v144
	v_pk_add_f32 v[84:85], v[84:85], v[178:179]
	v_pk_add_f32 v[82:83], v[82:83], v[174:175]
	v_cndmask_b32_e32 v94, v205, v94, vcc
	v_cmp_lt_i32_e32 vcc, -1, v228
	v_pk_add_f32 v[80:81], v[80:81], v[172:173]
	v_pk_add_f32 v[78:79], v[78:79], v[216:217]
	v_cndmask_b32_e32 v93, v205, v93, vcc
	v_cmp_lt_i32_e32 vcc, -1, v229
	v_pk_add_f32 v[76:77], v[76:77], v[196:197]
	v_pk_add_f32 v[74:75], v[74:75], v[192:193]
	v_cndmask_b32_e32 v92, v205, v92, vcc
	v_cmp_lt_i32_e32 vcc, -1, v226
	v_pk_add_f32 v[72:73], v[72:73], v[188:189]
	v_pk_add_f32 v[70:71], v[70:71], v[184:185]
	v_cndmask_b32_e32 v91, v205, v91, vcc
	v_cmp_lt_i32_e32 vcc, -1, v227
	v_pk_add_f32 v[68:69], v[68:69], v[180:181]
	v_pk_add_f32 v[66:67], v[66:67], v[176:177]
	v_cndmask_b32_e32 v90, v205, v90, vcc
	v_cmp_lt_i32_e32 vcc, -1, v224
	v_pk_add_f32 v[64:65], v[64:65], v[168:169]
	s_nop 0
	v_cndmask_b32_e32 v89, v205, v89, vcc
	v_cmp_lt_i32_e32 vcc, -1, v225
	s_nop 1
	v_cndmask_b32_e32 v88, v205, v88, vcc
	v_cmp_lt_i32_e32 vcc, -1, v222
	s_nop 1
	v_cndmask_b32_e32 v87, v205, v87, vcc
	v_cmp_lt_i32_e32 vcc, -1, v223
	s_nop 1
	v_cndmask_b32_e32 v86, v205, v86, vcc
	v_cmp_lt_i32_e32 vcc, -1, v220
	s_nop 1
	v_cndmask_b32_e32 v85, v205, v85, vcc
	v_cmp_lt_i32_e32 vcc, -1, v221
	s_nop 1
	v_cndmask_b32_e32 v84, v205, v84, vcc
	v_cmp_lt_i32_e32 vcc, -1, v218
	s_nop 1
	v_cndmask_b32_e32 v83, v205, v83, vcc
	v_cmp_lt_i32_e32 vcc, -1, v219
	s_nop 1
	v_cndmask_b32_e32 v82, v205, v82, vcc
	v_cmp_lt_i32_e32 vcc, -1, v161
	s_nop 1
	v_cndmask_b32_e32 v81, v205, v81, vcc
	v_cmp_lt_i32_e32 vcc, -1, v171
	s_nop 1
	v_cndmask_b32_e32 v80, v205, v80, vcc
	v_cmp_lt_i32_e32 vcc, 31, v230
	s_nop 1
	v_cndmask_b32_e32 v79, v205, v79, vcc
	v_cmp_lt_i32_e32 vcc, 31, v144
	s_nop 1
	v_cndmask_b32_e32 v78, v205, v78, vcc
	v_cmp_lt_i32_e32 vcc, 31, v228
	s_nop 1
	v_cndmask_b32_e32 v77, v205, v77, vcc
	v_cmp_lt_i32_e32 vcc, 31, v229
	s_nop 1
	v_cndmask_b32_e32 v76, v205, v76, vcc
	v_cmp_lt_i32_e32 vcc, 31, v226
	s_nop 1
	v_cndmask_b32_e32 v75, v205, v75, vcc
	v_cmp_lt_i32_e32 vcc, 31, v227
	s_nop 1
	v_cndmask_b32_e32 v74, v205, v74, vcc
	v_cmp_lt_i32_e32 vcc, 31, v224
	s_nop 1
	v_cndmask_b32_e32 v73, v205, v73, vcc
	v_cmp_lt_i32_e32 vcc, 31, v225
	s_nop 1
	v_cndmask_b32_e32 v72, v205, v72, vcc
	v_cmp_lt_i32_e32 vcc, 31, v222
	s_nop 1
	v_cndmask_b32_e32 v71, v205, v71, vcc
	v_cmp_lt_i32_e32 vcc, 31, v223
	s_nop 1
	v_cndmask_b32_e32 v70, v205, v70, vcc
	v_cmp_lt_i32_e32 vcc, 31, v220
	s_nop 1
	v_cndmask_b32_e32 v69, v205, v69, vcc
	v_cmp_lt_i32_e32 vcc, 31, v221
	s_nop 1
	v_cndmask_b32_e32 v68, v205, v68, vcc
	v_cmp_lt_i32_e32 vcc, 31, v218
	s_nop 1
	v_cndmask_b32_e32 v67, v205, v67, vcc
	v_cmp_lt_i32_e32 vcc, 31, v219
	s_nop 1
	v_cndmask_b32_e32 v66, v205, v66, vcc
	v_cmp_lt_i32_e32 vcc, 31, v161
	s_nop 1
	v_cndmask_b32_e32 v65, v205, v65, vcc
	v_cmp_lt_i32_e32 vcc, 31, v171
	s_nop 1
	v_cndmask_b32_e32 v64, v205, v64, vcc

; #define ALAS __attribute__((address_space(3)))
; __device__ __forceinline__ float ex2(float x) { return __builtin_amdgcn_exp2f(x); }
; template <int NDB> __device__ __forceinline__ void wait_v(bf16x8 (&v)[2 * NDB]) { if constexpr (NDB == 4) lds_wait8(v); else lds_wait4(v); }
; template <int NDB>
; __device__ __forceinline__ void softmax_pv(f32x16& s0, f32x16& s1, float& mref, float& lsum, f32x16 (&o)[NDB], const ALAS unsigned char* Vb, int r32, int hi) {
;     const unsigned vp = (unsigned)(uintptr_t)(Vb + r32 * ROWB + hi * 16);
;     bf16x8 va[2 * NDB], vb[2 * NDB];
;     issue_v<NDB, 0>(va, vp);
;     float ps = 0.f;
; #pragma unroll
;     for (int r = 0; r < 16; ++r) { s0[r] = ex2(s0[r]); ps += s0[r]; }
;     bf16x8 pf0, pf1, pf2, pf3;
;     pack16(s0, pf0, pf1);
;     wait_v<NDB>(va);
;     issue_v<NDB, 1>(vb, vp);
;     __builtin_amdgcn_sched_barrier(0);
; #pragma unroll
;     for (int d = 0; d < NDB; ++d) o[d] = __builtin_amdgcn_mfma_f32_32x32x16_bf16(va[d], pf0, o[d], 0, 0, 0);
; #pragma unroll
;     for (int d = 0; d < NDB; ++d) o[d] = __builtin_amdgcn_mfma_f32_32x32x16_bf16(va[NDB + d], pf1, o[d], 0, 0, 0);
; #pragma unroll
;     for (int r = 0; r < 16; ++r) { s1[r] = ex2(s1[r]); ps += s1[r]; }
;     pack16(s1, pf2, pf3);
; #pragma unroll
;     for (int i = 0; i < 2 * NDB; ++i) { __builtin_amdgcn_sched_group_barrier(0x008, 1, 0); __builtin_amdgcn_sched_group_barrier(0x002, (NDB == 4 ? 5 : 10), 0); }
;     __builtin_amdgcn_sched_barrier(0);
;     wait_v<NDB>(vb);
;     __builtin_amdgcn_sched_barrier(0);
; #pragma unroll
;     for (int d = 0; d < NDB; ++d) o[d] = __builtin_amdgcn_mfma_f32_32x32x16_bf16(vb[d], pf2, o[d], 0, 0, 0);
; #pragma unroll
;     for (int d = 0; d < NDB; ++d) o[d] = __builtin_amdgcn_mfma_f32_32x32x16_bf16(vb[NDB + d], pf3, o[d], 0, 0, 0);
;     lsum += ps;
;     if (__any(ps > 1048576.0f)) {
;         const float pt = ps + __shfl_xor(ps, 32); const float dl = pt > 1048576.0f ? floorf(__log2f(pt)) : 0.f, al = ex2(-dl); mref += dl; lsum *= al;
; #pragma unroll
;         for (int d = 0; d < NDB; ++d)
; #pragma unroll
;             for (int r = 0; r < 16; ++r) o[d][r] *= al;
;     }
.Lpv_d:
	s_waitcnt lgkmcnt(8)
	v_mfma_f32_32x32x16_bf16 v[48:63], v[172:175], v[80:83], v[48:63]
	v_add_f32_e32 v144, 0, v161
	v_add_f32_e32 v144, v168, v144
	v_add_f32_e32 v144, v169, v144
	v_add_f32_e32 v144, v171, v144
	v_add_f32_e32 v144, v244, v144
	v_exp_f32_e32 v161, v68
	v_exp_f32_e32 v168, v69
	v_mfma_f32_32x32x16_bf16 v[32:47], v[176:179], v[80:83], v[32:47]
	v_add_f32_e32 v144, v245, v144
	v_add_f32_e32 v144, v246, v144
	v_add_f32_e32 v144, v247, v144
	v_add_f32_e32 v144, v248, v144
	v_add_f32_e32 v144, v249, v144
	v_exp_f32_e32 v169, v70
	v_exp_f32_e32 v171, v71
	v_mfma_f32_32x32x16_bf16 v[16:31], v[180:183], v[80:83], v[16:31]
	v_add_f32_e32 v144, v250, v144
	v_add_f32_e32 v144, v251, v144
	v_add_f32_e32 v144, v252, v144
	v_add_f32_e32 v144, v253, v144
	v_add_f32_e32 v144, v215, v144
	v_exp_f32_e32 v72, v72
	v_exp_f32_e32 v73, v73
	v_mfma_f32_32x32x16_bf16 v[0:15], v[184:187], v[80:83], v[0:15]
	v_exp_f32_e32 v81, v64
	v_exp_f32_e32 v82, v65
	v_exp_f32_e32 v83, v66
	v_add_f32_e32 v80, v207, v144
	v_exp_f32_e32 v144, v67
	v_add_f32_e32 v80, v81, v80
	v_add_f32_e32 v80, v82, v80
	v_exp_f32_e32 v74, v74
	v_exp_f32_e32 v75, v75
	v_exp_f32_e32 v76, v76
	v_exp_f32_e32 v77, v77
	v_exp_f32_e32 v78, v78
	v_exp_f32_e32 v79, v79
	v_add_f32_e32 v80, v83, v80
	v_add_f32_e32 v80, v144, v80
	v_add_f32_e32 v80, v161, v80
	v_add_f32_e32 v80, v168, v80
	v_cvt_pk_bf16_f32 v64, v81, v82
	v_cvt_pk_bf16_f32 v65, v83, v144
	v_cvt_pk_bf16_f32 v66, v161, v168
	v_cvt_pk_bf16_f32 v67, v169, v171
	v_mfma_f32_32x32x16_bf16 v[48:63], v[188:191], v[84:87], v[48:63]
	v_cvt_pk_bf16_f32 v68, v72, v73
	v_cvt_pk_bf16_f32 v69, v74, v75
	v_cvt_pk_bf16_f32 v70, v76, v77
	v_cvt_pk_bf16_f32 v71, v78, v79
	v_add_f32_e32 v80, v169, v80
	v_add_f32_e32 v80, v171, v80
	v_add_f32_e32 v72, v72, v80
	v_mfma_f32_32x32x16_bf16 v[32:47], v[192:195], v[84:87], v[32:47]
	v_add_f32_e32 v72, v73, v72
	v_add_f32_e32 v72, v74, v72
	v_add_f32_e32 v72, v75, v72
	v_add_f32_e32 v72, v76, v72
	v_add_f32_e32 v72, v77, v72
	v_add_f32_e32 v72, v78, v72
	v_mfma_f32_32x32x16_bf16 v[16:31], v[196:199], v[84:87], v[16:31]
	v_mfma_f32_32x32x16_bf16 v[0:15], v[216:219], v[84:87], v[0:15]
	s_waitcnt lgkmcnt(0)
	s_nop 0
	v_mfma_f32_32x32x16_bf16 v[48:63], v[88:91], v[64:67], v[48:63]
	v_mfma_f32_32x32x16_bf16 v[32:47], v[92:95], v[64:67], v[32:47]
	v_mfma_f32_32x32x16_bf16 v[16:31], v[220:223], v[64:67], v[16:31]
	v_mfma_f32_32x32x16_bf16 v[0:15], v[224:227], v[64:67], v[0:15]
	v_add_f32_e32 v64, v79, v72
	v_add_f32_e32 v162, v162, v64
	v_cmp_lt_f32_e32 vcc, s34, v64
	v_mfma_f32_32x32x16_bf16 v[48:63], v[228:231], v[68:71], v[48:63]
	v_mfma_f32_32x32x16_bf16 v[32:47], v[232:235], v[68:71], v[32:47]
	v_mfma_f32_32x32x16_bf16 v[16:31], v[236:239], v[68:71], v[16:31]
	v_mfma_f32_32x32x16_bf16 v[0:15], v[240:243], v[68:71], v[0:15]
	s_cbranch_vccz .LBB0_503
	ds_bpermute_b32 v65, v170, v64
	s_waitcnt lgkmcnt(0)
	v_add_f32_e32 v64, v64, v65
	v_log_f32_e32 v65, v64
	v_cmp_lt_f32_e32 vcc, s34, v64
	v_floor_f32_e32 v65, v65
	s_nop 0
	v_cndmask_b32_e32 v65, 0, v65, vcc
	v_exp_f32_e64 v64, -v65
	v_add_f32_e32 v163, v163, v65
	v_mul_f32_e32 v162, v162, v64
	v_pk_mul_f32 v[62:63], v[62:63], v[64:65] op_sel_hi:[1,0]
	v_pk_mul_f32 v[60:61], v[60:61], v[64:65] op_sel_hi:[1,0]
	v_pk_mul_f32 v[58:59], v[58:59], v[64:65] op_sel_hi:[1,0]
	v_pk_mul_f32 v[56:57], v[56:57], v[64:65] op_sel_hi:[1,0]
	v_pk_mul_f32 v[54:55], v[54:55], v[64:65] op_sel_hi:[1,0]
	v_pk_mul_f32 v[52:53], v[52:53], v[64:65] op_sel_hi:[1,0]
	v_pk_mul_f32 v[50:51], v[50:51], v[64:65] op_sel_hi:[1,0]
	v_pk_mul_f32 v[48:49], v[48:49], v[64:65] op_sel_hi:[1,0]
	v_pk_mul_f32 v[46:47], v[46:47], v[64:65] op_sel_hi:[1,0]
	v_pk_mul_f32 v[44:45], v[44:45], v[64:65] op_sel_hi:[1,0]
	v_pk_mul_f32 v[42:43], v[42:43], v[64:65] op_sel_hi:[1,0]
	v_pk_mul_f32 v[40:41], v[40:41], v[64:65] op_sel_hi:[1,0]
	v_pk_mul_f32 v[38:39], v[38:39], v[64:65] op_sel_hi:[1,0]
	v_pk_mul_f32 v[36:37], v[36:37], v[64:65] op_sel_hi:[1,0]
	v_pk_mul_f32 v[34:35], v[34:35], v[64:65] op_sel_hi:[1,0]
	v_pk_mul_f32 v[32:33], v[32:33], v[64:65] op_sel_hi:[1,0]
	v_pk_mul_f32 v[30:31], v[30:31], v[64:65] op_sel_hi:[1,0]
	v_pk_mul_f32 v[28:29], v[28:29], v[64:65] op_sel_hi:[1,0]
	v_pk_mul_f32 v[26:27], v[26:27], v[64:65] op_sel_hi:[1,0]
	v_pk_mul_f32 v[24:25], v[24:25], v[64:65] op_sel_hi:[1,0]
	v_pk_mul_f32 v[22:23], v[22:23], v[64:65] op_sel_hi:[1,0]
	v_pk_mul_f32 v[20:21], v[20:21], v[64:65] op_sel_hi:[1,0]
	v_pk_mul_f32 v[18:19], v[18:19], v[64:65] op_sel_hi:[1,0]
	v_pk_mul_f32 v[16:17], v[16:17], v[64:65] op_sel_hi:[1,0]
	v_pk_mul_f32 v[14:15], v[14:15], v[64:65] op_sel_hi:[1,0]
	v_pk_mul_f32 v[12:13], v[12:13], v[64:65] op_sel_hi:[1,0]
	v_pk_mul_f32 v[10:11], v[10:11], v[64:65] op_sel_hi:[1,0]
	v_pk_mul_f32 v[8:9], v[8:9], v[64:65] op_sel_hi:[1,0]
	v_pk_mul_f32 v[6:7], v[6:7], v[64:65] op_sel_hi:[1,0]
	v_pk_mul_f32 v[4:5], v[4:5], v[64:65] op_sel_hi:[1,0]
	v_pk_mul_f32 v[2:3], v[2:3], v[64:65] op_sel_hi:[1,0]
	v_pk_mul_f32 v[0:1], v[0:1], v[64:65] op_sel_hi:[1,0]
	s_branch .LBB0_503
